# stack with the prompt-item wave stagger at s_sleep 40
# baseline (speedup 1.0000x reference)
; template <bool SAMPLE> ...
;     ...
; #pragma unroll
;     for (int d0 = 0; d0 < 4; ++d0) { const f32x4 g0 = *(const f32x4*)(qg + d0 * 16 + hi * 8), g1 = *(const f32x4*)(qg + d0 * 16 + hi * 8 + 4);
;         q[d0][0] *= rstd * g0.x; q[d0][1] *= rstd * g0.y; q[d0][2] *= rstd * g0.z; q[d0][3] *= rstd * g0.w; q[d0][4] *= rstd * g1.x; q[d0][5] *= rstd * g1.y; q[d0][6] *= rstd * g1.z; q[d0][7] *= rstd * g1.w; }
; __device__ __forceinline__ void attn_prompt_item(const Args& a, int l, int item, LAS unsigned char* lds, int tid, int lane, int wave) {
;     ...
;     __syncthreads();
;     attn_tile32<false>(qw0, zw0, Y, tab, qg, sinks, Kl + 32 * qt0 * 144, Vl + 32 * qt0 * 64, 16384, wsf, ost, rowq0, headw, b * 128 + qt0 * 32, (b == 0) ? 4 - qt0 : 0, lane);
;     attn_tile32<false>(qw1, zw1, Y, tab, qg, sinks, Kl + 32 * (qt0 + 1) * 144, Vl + 32 * (qt0 + 1) * 64, 16384, wsf, ost, rowq0 + 32, headw, b * 128 + qt0 * 32 + 32, (b == 0) ? 3 - qt0 : 0, lane);
.LBB0_475:
	s_or_b64 exec, exec, s[0:1]
	v_cmp_lt_i32_e32 vcc, v220, v214
	v_and_b32_e32 v172, 32, v132
	s_waitcnt lgkmcnt(0)
	v_cndmask_b32_e32 v16, v213, v220, vcc
	s_barrier
	v_lshlrev_b32_e32 v127, 2, v16
	global_load_dwordx4 v[16:19], v172, s[62:63]
	global_load_dwordx4 v[20:23], v172, s[62:63] offset:16
	global_load_dwordx4 v[24:27], v172, s[62:63] offset:64
	global_load_dwordx4 v[28:31], v172, s[62:63] offset:80
	global_load_dwordx4 v[32:35], v172, s[62:63] offset:128
	global_load_dwordx4 v[36:39], v172, s[62:63] offset:144
	global_load_dwordx4 v[40:43], v172, s[62:63] offset:192
	global_load_dwordx4 v[44:47], v172, s[62:63] offset:208
	v_readfirstlane_b32 s0, v208
	s_nop 3
	s_cmpk_lt_u32 s0, 0x100
	s_cbranch_scc1 .Lstg_skip
	s_sleep 40
